# grid barrier first check made order-safe (spin unless the XCD word is already ahead); otherwise same as previous version
# baseline (speedup 1.0000x reference)
.LBB0_178:
	s_or_b64 exec, exec, s[6:7]
	v_cvt_f32_u32_e32 v4, v2
	s_waitcnt vmcnt(0)
	v_readfirstlane_b32 s2, v3
	v_sub_u32_e32 v3, 0, v2
	v_rcp_iflag_f32_e32 v4, v4
	v_add_u32_e32 v5, s2, v1
	v_mul_f32_e32 v4, 0x4f7ffffe, v4
	v_cvt_u32_f32_e32 v4, v4
	v_mul_lo_u32 v1, v3, v4
	v_mul_hi_u32 v1, v4, v1
	v_add_u32_e32 v1, v4, v1
	v_mul_hi_u32 v1, v5, v1
	v_mul_lo_u32 v3, v1, v2
	v_sub_u32_e32 v3, v5, v3
	v_add_u32_e32 v4, 1, v1
	v_cmp_ge_u32_e32 vcc, v3, v2
	s_nop 1
	v_cndmask_b32_e32 v1, v1, v4, vcc
	v_sub_u32_e32 v4, v3, v2
	v_cndmask_b32_e32 v3, v3, v4, vcc
	v_add_u32_e32 v4, 1, v1
	v_cmp_ge_u32_e32 vcc, v3, v2
	v_add_u32_e32 v3, 1, v5
	s_nop 0
	v_cndmask_b32_e32 v1, v1, v4, vcc
	v_mul_lo_u32 v4, v2, v1
	v_add_u32_e32 v2, v4, v2
	v_cmp_ne_u32_e32 vcc, v3, v2
	s_and_saveexec_b64 s[2:3], vcc
	s_xor_b64 s[2:3], exec, s[2:3]
	s_cbranch_execz .LBB0_192
	s_waitcnt lgkmcnt(0)
	v_mov_b32_e32 v0, 0x2000
	global_load_dword v0, v0, s[4:5] offset:1024 sc1
	s_add_u32 s12, s4, 0x2400
	s_addc_u32 s13, s5, 0
	s_waitcnt vmcnt(0)
	v_cmp_le_u32_e32 vcc, v0, v1
	s_and_saveexec_b64 s[6:7], vcc
	s_cbranch_execz .LBB0_191
	s_add_u32 s10, s8, 0x8200
	s_addc_u32 s11, s9, 0
	s_add_u32 s12, s8, 0xb500
	s_addc_u32 s13, s9, 0
	s_mov_b32 s21, 1
	s_mov_b64 s[14:15], 0
	v_mov_b32_e32 v0, 0
	s_branch .LBB0_182

.LBB0_335:
	s_or_b64 exec, exec, s[8:9]
	v_cvt_f32_u32_e32 v4, v2
	s_waitcnt vmcnt(0)
	v_readfirstlane_b32 s2, v3
	v_sub_u32_e32 v3, 0, v2
	v_rcp_iflag_f32_e32 v4, v4
	v_add_u32_e32 v5, s2, v1
	v_mul_f32_e32 v4, 0x4f7ffffe, v4
	v_cvt_u32_f32_e32 v4, v4
	v_mul_lo_u32 v1, v3, v4
	v_mul_hi_u32 v1, v4, v1
	v_add_u32_e32 v1, v4, v1
	v_mul_hi_u32 v1, v5, v1
	v_mul_lo_u32 v3, v1, v2
	v_sub_u32_e32 v3, v5, v3
	v_add_u32_e32 v4, 1, v1
	v_cmp_ge_u32_e32 vcc, v3, v2
	s_nop 1
	v_cndmask_b32_e32 v1, v1, v4, vcc
	v_sub_u32_e32 v4, v3, v2
	v_cndmask_b32_e32 v3, v3, v4, vcc
	v_add_u32_e32 v4, 1, v1
	v_cmp_ge_u32_e32 vcc, v3, v2
	v_add_u32_e32 v3, 1, v5
	s_nop 0
	v_cndmask_b32_e32 v1, v1, v4, vcc
	v_mul_lo_u32 v4, v2, v1
	v_add_u32_e32 v2, v4, v2
	v_cmp_ne_u32_e32 vcc, v3, v2
	s_and_saveexec_b64 s[2:3], vcc
	s_xor_b64 s[2:3], exec, s[2:3]
	s_cbranch_execz .LBB0_349
	s_waitcnt lgkmcnt(0)
	v_mov_b32_e32 v0, 0x2000
	global_load_dword v0, v0, s[6:7] offset:1024 sc1
	s_add_u32 s14, s6, 0x2400
	s_addc_u32 s15, s7, 0
	s_waitcnt vmcnt(0)
	v_cmp_le_u32_e32 vcc, v0, v1
	s_and_saveexec_b64 s[8:9], vcc
	s_cbranch_execz .LBB0_348
	s_add_u32 s12, s0, 0x8200
	s_addc_u32 s13, s1, 0
	s_add_u32 s14, s0, 0xb500
	s_addc_u32 s15, s1, 0
	s_mov_b32 s28, 1
	s_mov_b64 s[16:17], 0
	v_mov_b32_e32 v0, 0
	s_branch .LBB0_339

.LBB0_657:
	s_or_b64 exec, exec, s[6:7]
	v_cvt_f32_u32_e32 v4, v2
	s_waitcnt vmcnt(0)
	v_readfirstlane_b32 s2, v3
	v_sub_u32_e32 v3, 0, v2
	v_rcp_iflag_f32_e32 v4, v4
	v_add_u32_e32 v5, s2, v1
	v_mul_f32_e32 v4, 0x4f7ffffe, v4
	v_cvt_u32_f32_e32 v4, v4
	v_mul_lo_u32 v1, v3, v4
	v_mul_hi_u32 v1, v4, v1
	v_add_u32_e32 v1, v4, v1
	v_mul_hi_u32 v1, v5, v1
	v_mul_lo_u32 v3, v1, v2
	v_sub_u32_e32 v3, v5, v3
	v_add_u32_e32 v4, 1, v1
	v_cmp_ge_u32_e32 vcc, v3, v2
	s_nop 1
	v_cndmask_b32_e32 v1, v1, v4, vcc
	v_sub_u32_e32 v4, v3, v2
	v_cndmask_b32_e32 v3, v3, v4, vcc
	v_add_u32_e32 v4, 1, v1
	v_cmp_ge_u32_e32 vcc, v3, v2
	v_add_u32_e32 v3, 1, v5
	s_nop 0
	v_cndmask_b32_e32 v1, v1, v4, vcc
	v_mul_lo_u32 v4, v2, v1
	v_add_u32_e32 v2, v4, v2
	v_cmp_ne_u32_e32 vcc, v3, v2
	s_and_saveexec_b64 s[2:3], vcc
	s_xor_b64 s[2:3], exec, s[2:3]
	s_cbranch_execz .LBB0_671
	s_waitcnt lgkmcnt(0)
	v_mov_b32_e32 v0, 0x2000
	global_load_dword v0, v0, s[4:5] offset:1024 sc1
	s_add_u32 s14, s4, 0x2400
	s_addc_u32 s15, s5, 0
	s_waitcnt vmcnt(0)
	v_cmp_le_u32_e32 vcc, v0, v1
	s_and_saveexec_b64 s[6:7], vcc
	s_cbranch_execz .LBB0_670
	s_add_u32 s12, s8, 0x8200
	s_addc_u32 s13, s9, 0
	s_add_u32 s14, s8, 0xb500
	s_addc_u32 s15, s9, 0
	s_mov_b32 s28, 1
	s_mov_b64 s[16:17], 0
	v_mov_b32_e32 v0, 0
	s_branch .LBB0_661

.LBB0_873:
	s_or_b64 exec, exec, s[6:7]
	v_cvt_f32_u32_e32 v4, v2
	s_waitcnt vmcnt(0)
	v_readfirstlane_b32 s2, v3
	v_sub_u32_e32 v3, 0, v2
	v_rcp_iflag_f32_e32 v4, v4
	v_add_u32_e32 v5, s2, v1
	v_mul_f32_e32 v4, 0x4f7ffffe, v4
	v_cvt_u32_f32_e32 v4, v4
	v_mul_lo_u32 v1, v3, v4
	v_mul_hi_u32 v1, v4, v1
	v_add_u32_e32 v1, v4, v1
	v_mul_hi_u32 v1, v5, v1
	v_mul_lo_u32 v3, v1, v2
	v_sub_u32_e32 v3, v5, v3
	v_add_u32_e32 v4, 1, v1
	v_cmp_ge_u32_e32 vcc, v3, v2
	s_nop 1
	v_cndmask_b32_e32 v1, v1, v4, vcc
	v_sub_u32_e32 v4, v3, v2
	v_cndmask_b32_e32 v3, v3, v4, vcc
	v_add_u32_e32 v4, 1, v1
	v_cmp_ge_u32_e32 vcc, v3, v2
	v_add_u32_e32 v3, 1, v5
	s_nop 0
	v_cndmask_b32_e32 v1, v1, v4, vcc
	v_mul_lo_u32 v4, v2, v1
	v_add_u32_e32 v2, v4, v2
	v_cmp_ne_u32_e32 vcc, v3, v2
	s_and_saveexec_b64 s[2:3], vcc
	s_xor_b64 s[2:3], exec, s[2:3]
	s_cbranch_execz .LBB0_887
	s_waitcnt lgkmcnt(0)
	v_mov_b32_e32 v0, 0x2000
	global_load_dword v0, v0, s[4:5] offset:1024 sc1
	s_add_u32 s12, s4, 0x2400
	s_addc_u32 s13, s5, 0
	s_waitcnt vmcnt(0)
	v_cmp_le_u32_e32 vcc, v0, v1
	s_and_saveexec_b64 s[6:7], vcc
	s_cbranch_execz .LBB0_886
	s_add_u32 s8, s18, 0x8200
	s_addc_u32 s9, s19, 0
	s_add_u32 s12, s18, 0xb500
	s_addc_u32 s13, s19, 0
	s_mov_b32 s28, 1
	s_mov_b64 s[14:15], 0
	v_mov_b32_e32 v0, 0
	s_branch .LBB0_877

.LBB0_983:
	s_or_b64 exec, exec, s[2:3]
	v_cvt_f32_u32_e32 v4, v2
	s_waitcnt vmcnt(0)
	v_readfirstlane_b32 s0, v3
	v_sub_u32_e32 v3, 0, v2
	v_rcp_iflag_f32_e32 v4, v4
	v_add_u32_e32 v5, s0, v1
	v_mul_f32_e32 v4, 0x4f7ffffe, v4
	v_cvt_u32_f32_e32 v4, v4
	v_mul_lo_u32 v1, v3, v4
	v_mul_hi_u32 v1, v4, v1
	v_add_u32_e32 v1, v4, v1
	v_mul_hi_u32 v1, v5, v1
	v_mul_lo_u32 v3, v1, v2
	v_sub_u32_e32 v3, v5, v3
	v_add_u32_e32 v4, 1, v1
	v_cmp_ge_u32_e32 vcc, v3, v2
	s_nop 1
	v_cndmask_b32_e32 v1, v1, v4, vcc
	v_sub_u32_e32 v4, v3, v2
	v_cndmask_b32_e32 v3, v3, v4, vcc
	v_add_u32_e32 v4, 1, v1
	v_cmp_ge_u32_e32 vcc, v3, v2
	v_add_u32_e32 v3, 1, v5
	s_nop 0
	v_cndmask_b32_e32 v1, v1, v4, vcc
	v_mul_lo_u32 v4, v2, v1
	v_add_u32_e32 v2, v4, v2
	v_cmp_ne_u32_e32 vcc, v3, v2
	s_and_saveexec_b64 s[0:1], vcc
	s_xor_b64 s[2:3], exec, s[0:1]
	s_cbranch_execz .LBB0_997
	s_waitcnt lgkmcnt(0)
	global_load_dword v0, v229, s[10:11] offset:1024 sc1
	s_add_u32 s12, s10, 0x2400
	s_addc_u32 s13, s11, 0
	s_waitcnt vmcnt(0)
	v_cmp_le_u32_e32 vcc, v0, v1
	s_and_saveexec_b64 s[0:1], vcc
	s_cbranch_execz .LBB0_996
	s_add_u32 s6, s78, 0x8200
	s_addc_u32 s7, s79, 0
	s_add_u32 s12, s78, 0xb500
	s_addc_u32 s13, s79, 0
	s_mov_b32 s26, 1
	s_mov_b64 s[16:17], 0
	s_branch .LBB0_987

.LBB0_1079:
	s_or_b64 exec, exec, s[2:3]
	v_cvt_f32_u32_e32 v4, v2
	s_waitcnt vmcnt(0)
	v_readfirstlane_b32 s0, v3
	v_sub_u32_e32 v3, 0, v2
	v_rcp_iflag_f32_e32 v4, v4
	v_add_u32_e32 v5, s0, v1
	v_mul_f32_e32 v4, 0x4f7ffffe, v4
	v_cvt_u32_f32_e32 v4, v4
	v_mul_lo_u32 v1, v3, v4
	v_mul_hi_u32 v1, v4, v1
	v_add_u32_e32 v1, v4, v1
	v_mul_hi_u32 v1, v5, v1
	v_mul_lo_u32 v3, v1, v2
	v_sub_u32_e32 v3, v5, v3
	v_add_u32_e32 v4, 1, v1
	v_cmp_ge_u32_e32 vcc, v3, v2
	s_nop 1
	v_cndmask_b32_e32 v1, v1, v4, vcc
	v_sub_u32_e32 v4, v3, v2
	v_cndmask_b32_e32 v3, v3, v4, vcc
	v_add_u32_e32 v4, 1, v1
	v_cmp_ge_u32_e32 vcc, v3, v2
	v_add_u32_e32 v3, 1, v5
	s_nop 0
	v_cndmask_b32_e32 v1, v1, v4, vcc
	v_mul_lo_u32 v4, v2, v1
	v_add_u32_e32 v2, v4, v2
	v_cmp_ne_u32_e32 vcc, v3, v2
	s_and_saveexec_b64 s[0:1], vcc
	s_xor_b64 s[2:3], exec, s[0:1]
	s_cbranch_execz .LBB0_1093
	s_waitcnt lgkmcnt(0)
	global_load_dword v0, v229, s[10:11] offset:1024 sc1
	s_add_u32 s12, s10, 0x2400
	s_addc_u32 s13, s11, 0
	s_waitcnt vmcnt(0)
	v_cmp_le_u32_e32 vcc, v0, v1
	s_and_saveexec_b64 s[6:7], vcc
	s_cbranch_execz .LBB0_1092
	s_add_u32 s8, s50, 0x8200
	s_addc_u32 s9, s51, 0
	s_add_u32 s12, s50, 0xb500
	s_addc_u32 s13, s51, 0
	s_mov_b32 s26, 1
	s_mov_b64 s[16:17], 0
	s_branch .LBB0_1083

.LBB0_1412:
	s_or_b64 exec, exec, s[2:3]
	v_cvt_f32_u32_e32 v4, v2
	s_waitcnt vmcnt(0)
	v_readfirstlane_b32 s0, v3
	v_sub_u32_e32 v3, 0, v2
	v_rcp_iflag_f32_e32 v4, v4
	v_add_u32_e32 v5, s0, v1
	v_mul_f32_e32 v4, 0x4f7ffffe, v4
	v_cvt_u32_f32_e32 v4, v4
	v_mul_lo_u32 v1, v3, v4
	v_mul_hi_u32 v1, v4, v1
	v_add_u32_e32 v1, v4, v1
	v_mul_hi_u32 v1, v5, v1
	v_mul_lo_u32 v3, v1, v2
	v_sub_u32_e32 v3, v5, v3
	v_add_u32_e32 v4, 1, v1
	v_cmp_ge_u32_e32 vcc, v3, v2
	s_nop 1
	v_cndmask_b32_e32 v1, v1, v4, vcc
	v_sub_u32_e32 v4, v3, v2
	v_cndmask_b32_e32 v3, v3, v4, vcc
	v_add_u32_e32 v4, 1, v1
	v_cmp_ge_u32_e32 vcc, v3, v2
	v_add_u32_e32 v3, 1, v5
	s_nop 0
	v_cndmask_b32_e32 v1, v1, v4, vcc
	v_mul_lo_u32 v4, v2, v1
	v_add_u32_e32 v2, v4, v2
	v_cmp_ne_u32_e32 vcc, v3, v2
	s_and_saveexec_b64 s[0:1], vcc
	s_xor_b64 s[2:3], exec, s[0:1]
	s_cbranch_execz .LBB0_1426
	s_waitcnt lgkmcnt(0)
	global_load_dword v0, v229, s[6:7] offset:1024 sc1
	s_add_u32 s10, s6, 0x2400
	s_addc_u32 s11, s7, 0
	s_waitcnt vmcnt(0)
	v_cmp_le_u32_e32 vcc, v0, v1
	s_and_saveexec_b64 s[0:1], vcc
	s_cbranch_execz .LBB0_1425
	v_readlane_b32 s8, v255, 34
	v_readlane_b32 s9, v255, 35
	s_add_u32 s8, s8, 0x8200
	s_addc_u32 s9, s9, 0
	s_add_u32 s10, s8, 0xb500
	s_addc_u32 s11, s9, 0
	s_mov_b32 s26, 1
	s_mov_b64 s[16:17], 0
	s_branch .LBB0_1416

.LBB0_1474:
	s_or_b64 exec, exec, s[6:7]
	v_cvt_f32_u32_e32 v4, v2
	s_waitcnt vmcnt(0)
	v_readfirstlane_b32 s2, v3
	v_sub_u32_e32 v3, 0, v2
	v_rcp_iflag_f32_e32 v4, v4
	v_add_u32_e32 v5, s2, v1
	v_mul_f32_e32 v4, 0x4f7ffffe, v4
	v_cvt_u32_f32_e32 v4, v4
	v_mul_lo_u32 v1, v3, v4
	v_mul_hi_u32 v1, v4, v1
	v_add_u32_e32 v1, v4, v1
	v_mul_hi_u32 v1, v5, v1
	v_mul_lo_u32 v3, v1, v2
	v_sub_u32_e32 v3, v5, v3
	v_add_u32_e32 v4, 1, v1
	v_cmp_ge_u32_e32 vcc, v3, v2
	s_nop 1
	v_cndmask_b32_e32 v1, v1, v4, vcc
	v_sub_u32_e32 v4, v3, v2
	v_cndmask_b32_e32 v3, v3, v4, vcc
	v_add_u32_e32 v4, 1, v1
	v_cmp_ge_u32_e32 vcc, v3, v2
	v_add_u32_e32 v3, 1, v5
	s_nop 0
	v_cndmask_b32_e32 v1, v1, v4, vcc
	v_mul_lo_u32 v4, v2, v1
	v_add_u32_e32 v2, v4, v2
	v_cmp_ne_u32_e32 vcc, v3, v2
	s_and_saveexec_b64 s[2:3], vcc
	s_xor_b64 s[2:3], exec, s[2:3]
	s_cbranch_execz .LBB0_1488
	s_waitcnt lgkmcnt(0)
	global_load_dword v0, v229, s[8:9] offset:1024 sc1
	s_add_u32 s12, s8, 0x2400
	s_addc_u32 s13, s9, 0
	s_waitcnt vmcnt(0)
	v_cmp_le_u32_e32 vcc, v0, v1
	s_and_saveexec_b64 s[6:7], vcc
	s_cbranch_execz .LBB0_1487
	s_add_u32 s10, s0, 0x8200
	s_addc_u32 s11, s1, 0
	s_add_u32 s12, s0, 0xb500
	s_addc_u32 s13, s1, 0
	s_mov_b32 s33, 1
	s_mov_b64 s[16:17], 0
	s_branch .LBB0_1478

.LBB0_1639:
	s_or_b64 exec, exec, s[2:3]
	v_cvt_f32_u32_e32 v4, v2
	s_waitcnt vmcnt(0)
	v_readfirstlane_b32 s0, v3
	v_sub_u32_e32 v3, 0, v2
	v_rcp_iflag_f32_e32 v4, v4
	v_add_u32_e32 v5, s0, v1
	v_mul_f32_e32 v4, 0x4f7ffffe, v4
	v_cvt_u32_f32_e32 v4, v4
	v_mul_lo_u32 v1, v3, v4
	v_mul_hi_u32 v1, v4, v1
	v_add_u32_e32 v1, v4, v1
	v_mul_hi_u32 v1, v5, v1
	v_mul_lo_u32 v3, v1, v2
	v_sub_u32_e32 v3, v5, v3
	v_add_u32_e32 v4, 1, v1
	v_cmp_ge_u32_e32 vcc, v3, v2
	s_nop 1
	v_cndmask_b32_e32 v1, v1, v4, vcc
	v_sub_u32_e32 v4, v3, v2
	v_cndmask_b32_e32 v3, v3, v4, vcc
	v_add_u32_e32 v4, 1, v1
	v_cmp_ge_u32_e32 vcc, v3, v2
	v_add_u32_e32 v3, 1, v5
	s_nop 0
	v_cndmask_b32_e32 v1, v1, v4, vcc
	v_mul_lo_u32 v4, v2, v1
	v_add_u32_e32 v2, v4, v2
	v_cmp_ne_u32_e32 vcc, v3, v2
	s_and_saveexec_b64 s[0:1], vcc
	s_xor_b64 s[2:3], exec, s[0:1]
	s_cbranch_execz .LBB0_1653
	s_waitcnt lgkmcnt(0)
	global_load_dword v0, v229, s[6:7] offset:1024 sc1
	s_add_u32 s10, s6, 0x2400
	s_addc_u32 s11, s7, 0
	s_waitcnt vmcnt(0)
	v_cmp_le_u32_e32 vcc, v0, v1
	s_and_saveexec_b64 s[0:1], vcc
	s_cbranch_execz .LBB0_1652
	s_add_u32 s8, s18, 0x8200
	s_addc_u32 s9, s19, 0
	s_add_u32 s10, s18, 0xb500
	s_addc_u32 s11, s19, 0
	s_mov_b32 s33, 1
	s_mov_b64 s[12:13], 0
	s_branch .LBB0_1643

.LBB0_1774:
	s_or_b64 exec, exec, s[2:3]
	v_cvt_f32_u32_e32 v4, v2
	s_waitcnt vmcnt(0)
	v_readfirstlane_b32 s0, v3
	v_sub_u32_e32 v3, 0, v2
	v_rcp_iflag_f32_e32 v4, v4
	v_add_u32_e32 v5, s0, v1
	v_mul_f32_e32 v4, 0x4f7ffffe, v4
	v_cvt_u32_f32_e32 v4, v4
	v_mul_lo_u32 v1, v3, v4
	v_mul_hi_u32 v1, v4, v1
	v_add_u32_e32 v1, v4, v1
	v_mul_hi_u32 v1, v5, v1
	v_mul_lo_u32 v3, v1, v2
	v_sub_u32_e32 v3, v5, v3
	v_add_u32_e32 v4, 1, v1
	v_cmp_ge_u32_e32 vcc, v3, v2
	s_nop 1
	v_cndmask_b32_e32 v1, v1, v4, vcc
	v_sub_u32_e32 v4, v3, v2
	v_cndmask_b32_e32 v3, v3, v4, vcc
	v_add_u32_e32 v4, 1, v1
	v_cmp_ge_u32_e32 vcc, v3, v2
	v_add_u32_e32 v3, 1, v5
	s_nop 0
	v_cndmask_b32_e32 v1, v1, v4, vcc
	v_mul_lo_u32 v4, v2, v1
	v_add_u32_e32 v2, v4, v2
	v_cmp_ne_u32_e32 vcc, v3, v2
	s_and_saveexec_b64 s[0:1], vcc
	s_xor_b64 s[2:3], exec, s[0:1]
	s_cbranch_execz .LBB0_1788
	s_waitcnt lgkmcnt(0)
	global_load_dword v0, v229, s[8:9] offset:1024 sc1
	s_add_u32 s16, s8, 0x2400
	s_addc_u32 s17, s9, 0
	s_waitcnt vmcnt(0)
	v_cmp_le_u32_e32 vcc, v0, v1
	s_and_saveexec_b64 s[10:11], vcc
	s_cbranch_execz .LBB0_1787
	s_add_u32 s12, s28, 0x8200
	s_addc_u32 s13, s29, 0
	s_add_u32 s16, s28, 0xb500
	s_addc_u32 s17, s29, 0
	s_mov_b32 s26, 1
	s_mov_b64 s[18:19], 0
	s_branch .LBB0_1778

.LBB0_1869:
	s_or_b64 exec, exec, s[2:3]
	v_cvt_f32_u32_e32 v4, v2
	s_waitcnt vmcnt(0)
	v_readfirstlane_b32 s0, v3
	v_sub_u32_e32 v3, 0, v2
	v_rcp_iflag_f32_e32 v4, v4
	v_add_u32_e32 v5, s0, v1
	v_mul_f32_e32 v4, 0x4f7ffffe, v4
	v_cvt_u32_f32_e32 v4, v4
	v_mul_lo_u32 v1, v3, v4
	v_mul_hi_u32 v1, v4, v1
	v_add_u32_e32 v1, v4, v1
	v_mul_hi_u32 v1, v5, v1
	v_mul_lo_u32 v3, v1, v2
	v_sub_u32_e32 v3, v5, v3
	v_add_u32_e32 v4, 1, v1
	v_cmp_ge_u32_e32 vcc, v3, v2
	s_nop 1
	v_cndmask_b32_e32 v1, v1, v4, vcc
	v_sub_u32_e32 v4, v3, v2
	v_cndmask_b32_e32 v3, v3, v4, vcc
	v_add_u32_e32 v4, 1, v1
	v_cmp_ge_u32_e32 vcc, v3, v2
	v_add_u32_e32 v3, 1, v5
	s_nop 0
	v_cndmask_b32_e32 v1, v1, v4, vcc
	v_mul_lo_u32 v4, v2, v1
	v_add_u32_e32 v2, v4, v2
	v_cmp_ne_u32_e32 vcc, v3, v2
	s_and_saveexec_b64 s[0:1], vcc
	s_xor_b64 s[2:3], exec, s[0:1]
	s_cbranch_execz .LBB0_1883
	s_waitcnt lgkmcnt(0)
	global_load_dword v0, v229, s[6:7] offset:1024 sc1
	s_add_u32 s12, s6, 0x2400
	s_addc_u32 s13, s7, 0
	s_waitcnt vmcnt(0)
	v_cmp_le_u32_e32 vcc, v0, v1
	s_and_saveexec_b64 s[8:9], vcc
	s_cbranch_execz .LBB0_1882
	s_add_u32 s10, s18, 0x8200
	s_addc_u32 s11, s19, 0
	s_add_u32 s12, s18, 0xb500
	s_addc_u32 s13, s19, 0
	s_mov_b32 s36, 1
	s_mov_b64 s[16:17], 0
	s_branch .LBB0_1873

.LBB0_1942:
	s_or_b64 exec, exec, s[2:3]
	v_cvt_f32_u32_e32 v4, v2
	s_waitcnt vmcnt(0)
	v_readfirstlane_b32 s0, v3
	v_sub_u32_e32 v3, 0, v2
	v_rcp_iflag_f32_e32 v4, v4
	v_add_u32_e32 v5, s0, v1
	v_mul_f32_e32 v4, 0x4f7ffffe, v4
	v_cvt_u32_f32_e32 v4, v4
	v_mul_lo_u32 v1, v3, v4
	v_mul_hi_u32 v1, v4, v1
	v_add_u32_e32 v1, v4, v1
	v_mul_hi_u32 v1, v5, v1
	v_mul_lo_u32 v3, v1, v2
	v_sub_u32_e32 v3, v5, v3
	v_add_u32_e32 v4, 1, v1
	v_cmp_ge_u32_e32 vcc, v3, v2
	s_nop 1
	v_cndmask_b32_e32 v1, v1, v4, vcc
	v_sub_u32_e32 v4, v3, v2
	v_cndmask_b32_e32 v3, v3, v4, vcc
	v_add_u32_e32 v4, 1, v1
	v_cmp_ge_u32_e32 vcc, v3, v2
	v_add_u32_e32 v3, 1, v5
	s_nop 0
	v_cndmask_b32_e32 v1, v1, v4, vcc
	v_mul_lo_u32 v4, v2, v1
	v_add_u32_e32 v2, v4, v2
	v_cmp_ne_u32_e32 vcc, v3, v2
	s_and_saveexec_b64 s[0:1], vcc
	s_xor_b64 s[2:3], exec, s[0:1]
	s_cbranch_execz .LBB0_1956
	s_waitcnt lgkmcnt(0)
	global_load_dword v0, v229, s[8:9] offset:1024 sc1
	s_add_u32 s16, s8, 0x2400
	s_addc_u32 s17, s9, 0
	s_waitcnt vmcnt(0)
	v_cmp_le_u32_e32 vcc, v0, v1
	s_and_saveexec_b64 s[10:11], vcc
	s_cbranch_execz .LBB0_1955
	s_add_u32 s12, s28, 0x8200
	s_addc_u32 s13, s29, 0
	s_add_u32 s16, s28, 0xb500
	s_addc_u32 s17, s29, 0
	s_mov_b32 s36, 1
	s_mov_b64 s[18:19], 0
	s_branch .LBB0_1946

.LBB0_2071:
	s_or_b64 exec, exec, s[2:3]
	v_cvt_f32_u32_e32 v4, v2
	s_waitcnt vmcnt(0)
	v_readfirstlane_b32 s0, v3
	v_sub_u32_e32 v3, 0, v2
	v_rcp_iflag_f32_e32 v4, v4
	v_add_u32_e32 v5, s0, v1
	v_mul_f32_e32 v4, 0x4f7ffffe, v4
	v_cvt_u32_f32_e32 v4, v4
	v_mul_lo_u32 v1, v3, v4
	v_mul_hi_u32 v1, v4, v1
	v_add_u32_e32 v1, v4, v1
	v_mul_hi_u32 v1, v5, v1
	v_mul_lo_u32 v3, v1, v2
	v_sub_u32_e32 v3, v5, v3
	v_add_u32_e32 v4, 1, v1
	v_cmp_ge_u32_e32 vcc, v3, v2
	s_nop 1
	v_cndmask_b32_e32 v1, v1, v4, vcc
	v_sub_u32_e32 v4, v3, v2
	v_cndmask_b32_e32 v3, v3, v4, vcc
	v_add_u32_e32 v4, 1, v1
	v_cmp_ge_u32_e32 vcc, v3, v2
	v_add_u32_e32 v3, 1, v5
	s_nop 0
	v_cndmask_b32_e32 v1, v1, v4, vcc
	v_mul_lo_u32 v4, v2, v1
	v_add_u32_e32 v2, v4, v2
	v_cmp_ne_u32_e32 vcc, v3, v2
	s_and_saveexec_b64 s[0:1], vcc
	s_xor_b64 s[2:3], exec, s[0:1]
	s_cbranch_execz .LBB0_2085
	s_waitcnt lgkmcnt(0)
	global_load_dword v0, v229, s[6:7] offset:1024 sc1
	s_add_u32 s12, s6, 0x2400
	s_addc_u32 s13, s7, 0
	s_waitcnt vmcnt(0)
	v_cmp_le_u32_e32 vcc, v0, v1
	s_and_saveexec_b64 s[8:9], vcc
	s_cbranch_execz .LBB0_2084
	s_add_u32 s10, s18, 0x8200
	s_addc_u32 s11, s19, 0
	s_add_u32 s12, s18, 0xb500
	s_addc_u32 s13, s19, 0
	s_mov_b32 s33, 1
	s_mov_b64 s[16:17], 0
	s_branch .LBB0_2075

.LBB0_2134:
	s_or_b64 exec, exec, s[8:9]
	v_cvt_f32_u32_e32 v4, v2
	s_waitcnt vmcnt(0)
	v_readfirstlane_b32 s6, v3
	v_sub_u32_e32 v3, 0, v2
	v_rcp_iflag_f32_e32 v4, v4
	v_add_u32_e32 v5, s6, v1
	v_mul_f32_e32 v4, 0x4f7ffffe, v4
	v_cvt_u32_f32_e32 v4, v4
	v_mul_lo_u32 v1, v3, v4
	v_mul_hi_u32 v1, v4, v1
	v_add_u32_e32 v1, v4, v1
	v_mul_hi_u32 v1, v5, v1
	v_mul_lo_u32 v3, v1, v2
	v_sub_u32_e32 v3, v5, v3
	v_add_u32_e32 v4, 1, v1
	v_cmp_ge_u32_e32 vcc, v3, v2
	s_nop 1
	v_cndmask_b32_e32 v1, v1, v4, vcc
	v_sub_u32_e32 v4, v3, v2
	v_cndmask_b32_e32 v3, v3, v4, vcc
	v_add_u32_e32 v4, 1, v1
	v_cmp_ge_u32_e32 vcc, v3, v2
	v_add_u32_e32 v3, 1, v5
	s_nop 0
	v_cndmask_b32_e32 v1, v1, v4, vcc
	v_mul_lo_u32 v4, v2, v1
	v_add_u32_e32 v2, v4, v2
	v_cmp_ne_u32_e32 vcc, v3, v2
	s_and_saveexec_b64 s[6:7], vcc
	s_xor_b64 s[6:7], exec, s[6:7]
	s_cbranch_execz .LBB0_2148
	s_waitcnt lgkmcnt(0)
	v_mov_b32_e32 v0, 0x2000
	global_load_dword v0, v0, s[4:5] offset:1024 sc1
	s_add_u32 s12, s4, 0x2400
	s_addc_u32 s13, s5, 0
	s_waitcnt vmcnt(0)
	v_cmp_le_u32_e32 vcc, v0, v1
	s_and_saveexec_b64 s[8:9], vcc
	s_cbranch_execz .LBB0_2147
	s_add_u32 s10, s2, 0x8200
	s_addc_u32 s11, s3, 0
	s_add_u32 s12, s2, 0xb500
	s_addc_u32 s13, s3, 0
	s_mov_b32 s24, 1
	s_mov_b64 s[14:15], 0
	v_mov_b32_e32 v0, 0
	s_branch .LBB0_2138
